# WQLT dot-product loads batched; kc_item loads batched; dequeue atomic issued before barrier; first grid barrier via XCD barrier; static prio raise waves 4-7 in MLA attention
# speedup vs baseline: 1.0188x; 1.0188x over previous
; DEVI void xcd_barrier(const XcdBarrier& b) {
;     asm volatile("s_waitcnt vmcnt(0)" ::: "memory");
;     __syncthreads();
;     if (threadIdx.x == 0) {
;         unsigned* bar = b.bar;
;         __builtin_amdgcn_s_waitcnt(0);
;         unsigned nloc = b.st[0], nx = b.st[1];
;         if (nloc == 0u) { xcd_barrier_complete(bar, b.x, nloc, nx); b.st[0] = nloc; b.st[1] = nx; }
; __global__ void __launch_bounds__(512) mega(Params p, int ph_lo, int ph_hi, int coop) {
;     ...
;     for (int ph = ph_lo; ph < ph_hi; ++ph) {
;         if (ph > ph_lo && coop) { if (ph == 1) cg::this_grid().sync(); else xcd_barrier(xb); }
.LBB0_9:
	v_writelane_b32 v255, s3, 22
	s_cmp_le_i32 s3, s28
	v_readlane_b32 s6, v255, 12
	s_cselect_b64 s[0:1], -1, 0
	v_readlane_b32 s7, v255, 13
	s_or_b64 s[0:1], s[6:7], s[0:1]
	s_and_b64 vcc, exec, s[0:1]
	s_cbranch_vccnz .LBB0_77
	v_readlane_b32 s0, v255, 22
	s_cmp_lg_u32 s0, 1
	s_mov_b64 s[0:1], -1
	s_nop 0
	s_waitcnt vmcnt(0)
	s_barrier
	s_and_saveexec_b64 s[0:1], s[82:83]
	s_cbranch_execz .LBB0_63
	v_mov_b32_e32 v0, 0x20010
	s_waitcnt vmcnt(0) expcnt(0) lgkmcnt(0)
	ds_read_b32 v3, v0
	v_mov_b32_e32 v0, 0x20014
	ds_read_b32 v2, v0
	s_waitcnt lgkmcnt(1)
	v_cmp_ne_u32_e32 vcc, 0, v3
	s_cbranch_vccnz .LBB0_27
	v_readlane_b32 s8, v251, 16
	v_readlane_b32 s9, v251, 17
	s_load_dwordx2 s[6:7], s[8:9], 0x0
	s_load_dword s3, s[8:9], 0x8
	s_mov_b32 s16, 1
	s_waitcnt lgkmcnt(0)
	s_mul_i32 s6, s7, s6
	s_mul_i32 s3, s6, s3
	s_branch .LBB0_15

; template <int MODE>
; DEVI void attn_item(const Params& p, int item, unsigned char* smem) {
;     ...
;     } else if constexpr (MODE == 1) {
;         wactive = true; qpos = q0 + wv * 32 + r; orow = (size_t)(b * 2048 + qpos);
;         const bf16_t* qp = QF + orow * 768 + hd * 96;
; #pragma unroll
;         for (int st = 0; st < KS; ++st) qf[st] = *(const bf16x8*)(qp + st * 16 + 8 * h);
;     ...
;     auto issue = [&](int kT) {
; #pragma unroll
;         for (int hf = 0; hf < NH; ++hf) {
;             const int kt = kT * NH + hf;
; #pragma unroll
;             for (int i = 0; i < NST; ++i) {
;                 u32x4 w = {0u, 0u, 0u, 0u};
;                 if constexpr (MODE == 0) {
;                     const int row = tid >> 3, ch = tid & 7, kk = kt * 64 + row;
;                     const int off = (i == 0 ? 512 : 1024) + hd * 64 + ch * 8;
;                     if (!samp) w = *(const u32x4*)(QKVG + (size_t)(b * 2048 + kk) * 3072 + off);
;                     else if (kk < 4096) w = ld_f32x8_bf16(p.in[i == 0 ? 2 : 3] + (((size_t)b * 4096 + kk) * 8 + hd) * 64 + ch * 8);
;                     else if (kk < 4112) w = *(const u32x4*)(QKVG + (size_t)(NP + b * 16 + kk - 4096) * 3072 + off);
;                 } else if constexpr (MODE == 1) {
;                     if (i == 0) { const int row = tid >> 3, ch = tid & 7; w = *(const u32x4*)(KVUP + (size_t)(b * 2048 + kt * 64 + row) * 1024 + 512 + hd * 64 + ch * 8); }
;                     else {
;                         const int id = tid + (i - 1) * 512;
;                         if (id < 768) { const int row = id / 12, ch = id % 12; const size_t gr = (size_t)(b * 2048 + kt * 64 + row);
;                             w = ch < 8 ? *(const u32x4*)(KVUP + gr * 1024 + hd * 64 + ch * 8) : *(const u32x4*)(IN1 + gr * 1792 + 1664 + (ch - 8) * 8); }
;                     }
.LBB0_193:
	s_and_b64 vcc, exec, s[0:1]
	s_cbranch_vccz .LBB0_268
	v_mov_b32_e32 v19, v180
	v_readfirstlane_b32 s0, v180
	s_cmp_lt_u32 s0, 0x100
	s_cbranch_scc1 .Lprio_m1
	s_setprio 1
.Lprio_m1:
	s_andn2_b32 s3, 0x700, s69
	s_lshr_b32 s0, s3, 6
	v_ashrrev_i32_e32 v0, 1, v19
	s_or_b32 s14, s0, 3
	v_and_b32_e32 v0, 0xffffffe0, v0
	s_lshl_b32 s0, s68, 7
	v_and_b32_e32 v20, 31, v19
	v_add_u32_e32 v22, s3, v0
	s_and_b32 s9, s0, 0xf800
	v_readlane_b32 s0, v252, 8
	s_lshr_b32 s73, s14, 1
	v_or_b32_e32 v26, v22, v20
	v_readlane_b32 s1, v252, 9
	s_lshl_b32 s8, s73, 7
	v_add_u32_e32 v150, s9, v26
	v_mov_b64_e32 v[2:3], s[0:1]
	s_movk_i32 s0, 0x600
	v_ashrrev_i32_e32 v18, 3, v19
	s_or_b32 s15, s8, s9
	s_bfe_u32 s16, s68, 0x30001
	v_mad_i64_i32 v[2:3], s[0:1], v150, s0, v[2:3]
	v_add_u32_e32 v10, s15, v18
	v_bfe_u32 v21, v19, 5, 1
	s_mul_i32 s24, s16, 0xc0
	v_ashrrev_i32_e32 v11, 31, v10
	v_readlane_b32 s0, v252, 10
	v_lshl_add_u64 v[2:3], v[2:3], 0, s[24:25]
	v_lshlrev_b32_e32 v0, 4, v21
	v_lshlrev_b64 v[10:11], 11, v[10:11]
	v_readlane_b32 s1, v252, 11
	v_lshl_add_u64 v[2:3], v[2:3], 0, v[0:1]
	s_lshl_b32 s24, s16, 7
	v_lshl_add_u64 v[12:13], s[0:1], 0, v[10:11]
	global_load_dwordx4 v[100:103], v[2:3], off
	global_load_dwordx4 v[104:107], v[2:3], off offset:32
	global_load_dwordx4 v[108:111], v[2:3], off offset:64
	global_load_dwordx4 v[112:115], v[2:3], off offset:96
	global_load_dwordx4 v[6:9], v[2:3], off offset:128
	s_nop 0
	global_load_dwordx4 v[2:5], v[2:3], off offset:160
	v_lshl_add_u64 v[14:15], v[12:13], 0, s[24:25]
	v_lshlrev_b32_e32 v12, 3, v19
	v_and_b32_e32 v12, 56, v12
	v_lshlrev_b32_e32 v12, 1, v12
	v_mov_b32_e32 v13, v1
	v_lshl_add_u64 v[14:15], v[14:15], 0, v[12:13]
	global_load_dwordx4 v[116:119], v[14:15], off offset:1024
	s_movk_i32 s0, 0x300
	v_cmp_gt_i32_e32 vcc, s0, v19
	s_mov_b32 s0, 0x2aaaaaab
	v_mul_hi_i32 v13, v19, s0
	s_lshl_b32 s16, s16, 6
	s_waitcnt vmcnt(0)
	v_mov_b32_e32 v120, v1
	v_mov_b32_e32 v121, v1
	v_mov_b32_e32 v122, v1
	v_mov_b32_e32 v123, v1
	v_lshrrev_b32_e32 v23, 31, v13
	v_ashrrev_i32_e32 v24, 1, v13
	s_and_saveexec_b64 s[38:39], vcc
	s_cbranch_execz .LBB0_200
	v_add_u32_e32 v14, v24, v23
	v_mul_lo_u32 v13, v14, 12
	v_sub_u32_e32 v13, v19, v13
	v_add_u32_e32 v14, s15, v14
	v_ashrrev_i32_e32 v15, 31, v14
	v_cmp_lt_i32_e64 s[0:1], 7, v13
	s_and_saveexec_b64 s[18:19], s[0:1]
	s_xor_b64 s[0:1], exec, s[18:19]
	v_mov_b64_e32 v[16:17], s[22:23]
	s_movk_i32 s17, 0xe00
	v_mad_i64_i32 v[14:15], s[18:19], v14, s17, v[16:17]
	v_lshlrev_b32_e32 v16, 4, v13
	v_mov_b32_e32 v17, v1
	v_lshl_add_u64 v[14:15], v[14:15], 0, v[16:17]
	s_mov_b64 s[18:19], 0xc80
	v_lshl_add_u64 v[16:17], v[14:15], 0, s[18:19]
	s_andn2_saveexec_b64 s[0:1], s[0:1]
	s_cbranch_execz .LBB0_199
	v_readlane_b32 s18, v252, 10
	v_lshlrev_b64 v[14:15], 11, v[14:15]
	v_readlane_b32 s19, v252, 11
	s_lshl_b32 s24, s16, 1
	v_lshlrev_b32_e32 v16, 3, v13
	v_lshl_add_u64 v[14:15], s[18:19], 0, v[14:15]
	v_lshl_add_u64 v[14:15], v[14:15], 0, s[24:25]
	v_ashrrev_i32_e32 v17, 31, v16
	v_lshl_add_u64 v[16:17], v[16:17], 1, v[14:15]

; template <int MODE>
; DEVI void attn_item(const Params& p, int item, unsigned char* smem) {
;     ...
;     if (MODE == 0 || MODE == 1) {
;         float inv = 1.f;
;         if constexpr (MODE == 1) { const float l = lrun + __shfl_xor(lrun, 32); inv = 1.f / l; }
;         if (wactive && qvalid) {
;             bf16_t* op = (MODE == 0) ? (bf16_t*)(p.ws + WS_R1 + R1_MIXED) + orow * 1024 + hd * 64
;                                      : (bf16_t*)(p.ws + WS_R1 + R1_MIXED2) + orow * 1024 + 512 + hd * 64;
; #pragma unroll
;             for (int d = 0; d < DB; ++d)
; #pragma unroll
;                 for (int g = 0; g < 4; ++g) {
;                     u32x2 w; w.x = pk2(O[d][4 * g] * inv, O[d][4 * g + 1] * inv); w.y = pk2(O[d][4 * g + 2] * inv, O[d][4 * g + 3] * inv);
;                     *(u32x2*)(op + d * 32 + 8 * g + 4 * h) = w;
;                 }
.LBB0_332:
	v_cmp_lt_i32_e32 vcc, v174, v173
	v_lshlrev_b64 v[2:3], 11, v[150:151]
	v_lshl_add_u64 v[2:3], s[96:97], 0, v[2:3]
	v_cndmask_b32_e32 v0, v172, v174, vcc
	v_lshlrev_b32_e32 v0, 2, v0
	ds_bpermute_b32 v0, v0, v197
	v_lshl_add_u64 v[2:3], v[2:3], 0, s[24:25]
	s_waitcnt lgkmcnt(0)
	v_add_f32_e32 v0, v197, v0
	v_div_scale_f32 v36, s[0:1], v0, v0, 1.0
	v_rcp_f32_e32 v37, v36
	v_div_scale_f32 v38, vcc, 1.0, v0, 1.0
	s_mov_b64 s[0:1], 0x33fdc400
	v_fma_f32 v39, -v36, v37, 1.0
	v_fmac_f32_e32 v37, v39, v37
	v_mul_f32_e32 v39, v38, v37
	v_fma_f32 v40, -v36, v39, v38
	v_fmac_f32_e32 v39, v40, v37
	v_fma_f32 v36, -v36, v39, v38
	v_div_fmas_f32 v36, v36, v37, v39
	v_div_fixup_f32 v38, v36, v0, 1.0
	v_lshlrev_b32_e32 v0, 1, v187
	v_lshl_add_u64 v[2:3], v[2:3], 0, v[0:1]
	v_lshl_add_u64 v[36:37], v[2:3], 0, s[0:1]
	v_mul_f32_e32 v0, v20, v38
	v_mul_f32_e32 v20, v21, v38
	s_mov_b32 s0, 0x33fdc000
	v_cvt_pk_bf16_f32 v20, v0, v20
	v_mul_f32_e32 v0, v22, v38
	v_mul_f32_e32 v21, v23, v38
	v_add_co_u32_e32 v2, vcc, s0, v2
	v_cvt_pk_bf16_f32 v21, v0, v21
	s_nop 0
	v_addc_co_u32_e32 v3, vcc, 0, v3, vcc
	global_store_dwordx2 v[2:3], v[20:21], off offset:1024
	v_mul_f32_e32 v0, v24, v38
	v_mul_f32_e32 v2, v25, v38
	v_cvt_pk_bf16_f32 v2, v0, v2
	v_mul_f32_e32 v0, v26, v38
	v_mul_f32_e32 v3, v27, v38
	v_cvt_pk_bf16_f32 v3, v0, v3
	global_store_dwordx2 v[36:37], v[2:3], off offset:16
	v_mul_f32_e32 v0, v28, v38
	v_mul_f32_e32 v2, v29, v38
	v_cvt_pk_bf16_f32 v2, v0, v2
	v_mul_f32_e32 v0, v30, v38
	v_mul_f32_e32 v3, v31, v38
	v_cvt_pk_bf16_f32 v3, v0, v3
	global_store_dwordx2 v[36:37], v[2:3], off offset:32
	v_mul_f32_e32 v0, v32, v38
	v_mul_f32_e32 v2, v33, v38
	v_cvt_pk_bf16_f32 v2, v0, v2
	v_mul_f32_e32 v0, v34, v38
	v_mul_f32_e32 v3, v35, v38
	v_cvt_pk_bf16_f32 v3, v0, v3
	global_store_dwordx2 v[36:37], v[2:3], off offset:48
	v_mul_f32_e32 v0, v4, v38
	v_mul_f32_e32 v2, v5, v38
	v_cvt_pk_bf16_f32 v2, v0, v2
	v_mul_f32_e32 v0, v6, v38
	v_mul_f32_e32 v3, v7, v38
	v_cvt_pk_bf16_f32 v3, v0, v3
	global_store_dwordx2 v[36:37], v[2:3], off offset:64
	v_mul_f32_e32 v0, v8, v38
	v_mul_f32_e32 v2, v9, v38
	v_cvt_pk_bf16_f32 v2, v0, v2
	v_mul_f32_e32 v0, v10, v38
	v_mul_f32_e32 v3, v11, v38
	v_cvt_pk_bf16_f32 v3, v0, v3
	global_store_dwordx2 v[36:37], v[2:3], off offset:80
	v_mul_f32_e32 v0, v12, v38
	v_mul_f32_e32 v2, v13, v38
	v_cvt_pk_bf16_f32 v2, v0, v2
	v_mul_f32_e32 v0, v14, v38
	v_mul_f32_e32 v3, v15, v38
	v_cvt_pk_bf16_f32 v3, v0, v3
	global_store_dwordx2 v[36:37], v[2:3], off offset:96
	v_mul_f32_e32 v0, v16, v38
	v_mul_f32_e32 v2, v17, v38
	v_cvt_pk_bf16_f32 v2, v0, v2
	v_mul_f32_e32 v0, v18, v38
	v_mul_f32_e32 v3, v19, v38
	v_cvt_pk_bf16_f32 v3, v0, v3
	global_store_dwordx2 v[36:37], v[2:3], off offset:112
	s_setprio 0
	s_cbranch_execz .LBB0_270
	s_branch .LBB0_104

; #define G_STAGE(bufoff, gbase, voff) do { _Pragma("unroll") for (int _i = 0; _i < 2; ++_i) \
;         __builtin_amdgcn_global_load_lds((const unsigned*)((const char*)(gbase) + (voff)[_i]), (LAS unsigned*)(lds + (bufoff) + ldsw + _i * 8192), 16, 0, 0); } while (0)
; #define G_WAIT_V(n) asm volatile("s_waitcnt vmcnt(" #n ")" ::: "memory")
; #define G_BAR __builtin_amdgcn_s_barrier()
; template <int NSTORE, class TF, class F>
; DEVI void gemm_run(const bf16_t* __restrict__ A, int lda, const bf16_t* __restrict__ Bt, int ldb, int K, bf16_t* shm, TF&& tile, F&& emit) {
;     ...
;     const int aoff = lds_byte(wr * 64 + fr, fq * 8), boff = lds_byte(wc * 32 + fr, fq * 8);
;     constexpr int HTB = HALF * BK * 2;
;     ...
;     int brow, bcol, nrow, ncol; int ui = 0;
;     if (!tile(0, brow, bcol)) return;
;     f32x4 acc[2][2][4][2];
; #pragma unroll
;     for (int a = 0; a < 2; ++a)
; #pragma unroll
;         for (int b = 0; b < 2; ++b)
; #pragma unroll
;             for (int m = 0; m < 4; ++m)
; #pragma unroll
;                 for (int n = 0; n < 2; ++n) acc[a][b][m][n] = (f32x4){0.f, 0.f, 0.f, 0.f};
;     bf16x8 At[4][2], B0[2][2], B1[2][2];
;     const char* cA = (const char*)A + (size_t)brow * lda * 2; const char* cB = (const char*)Bt + (size_t)bcol * ldb * 2;
;     G_STAGE(G_SB(0, 0), cB, voffB); G_STAGE(G_SB(0, 1), cB + hstepB, voffB); G_STAGE(G_SA(0, 0), cA, voffA); G_STAGE(G_SA(0, 1), cA + hstepA, voffA);
;     if (wr == 1) G_BAR;
;     G_WAIT_V(2); G_BAR;
;     G_STAGE(G_SB(1, 0), cB + kstep, voffB); G_STAGE(G_SA(1, 0), cA + kstep, voffA); G_STAGE(G_SB(1, 1), cB + hstepB + kstep, voffB);
;     G_WAIT_V(6); G_BAR;
; DEVI void kc_item(const Params& p, int item) {
;     ...
;     for (int e = 0; e < 8; ++e) {
;         const long id = (long)item * 4096 + e * 512 + tid;
;         const long rw = id / 36; const int ch = (int)(id - rw * 36);
;         const int b = (int)(rw >> 12), kk = (int)(rw & 4095);
;         const float* src = ch < 32 ? cc + (size_t)rw * 256 + ch * 8 : cp + (size_t)rw * 32 + (ch - 32) * 8;
;         f32x4 a = *(const f32x4*)src, bb = *(const f32x4*)(src + 4);
;         u32x4 w; w.x = pk2(a[0], a[1]); w.y = pk2(a[2], a[3]); w.z = pk2(bb[0], bb[1]); w.w = pk2(bb[2], bb[3]);
;         *(u32x4*)(KC + ((size_t)b * 4112 + kk) * 288 + ch * 8) = w;
.LBB0_562:
	v_lshrrev_b32_e32 v18, 1, v8
	v_readlane_b32 s42, v254, 50
	v_and_b32_e32 v18, 24, v18
	s_lshl_b32 s6, s6, 5
	v_readlane_b32 s43, v254, 51
	v_and_b32_e32 v9, 15, v8
	v_lshlrev_b32_e32 v19, 1, v18
	v_lshlrev_b32_e32 v8, 2, v8
	s_and_b32 s8, s6, 0x60
	v_lshl_add_u64 v[10:11], s[42:43], 0, v[0:1]
	v_mov_b32_e32 v131, v1
	v_readlane_b32 s40, v254, 46
	v_lshl_or_b32 v140, s7, 6, v9
	v_lshl_or_b32 v9, v9, 6, v19
	s_lshl_b32 s7, s7, 13
	v_and_b32_e32 v8, 32, v8
	s_lshl_b32 s6, s8, 7
	s_add_i32 s26, s46, 0x18000
	v_lshl_add_u64 v[12:13], s[42:43], 0, v[130:131]
	v_mov_b32_e32 v135, v1
	v_readlane_b32 s41, v254, 47
	v_bitop3_b32 v141, v9, s7, v8 bitop3:0xde
	v_bitop3_b32 v142, v9, s6, v8 bitop3:0xde
	v_lshl_add_u64 v[8:9], v[10:11], 0, s[30:31]
	s_mov_b32 m0, s26
	s_add_i32 s27, s46, 0x1a000
	v_lshl_add_u64 v[14:15], s[40:41], 0, v[134:135]
	v_mov_b32_e32 v133, v1
	s_waitcnt vmcnt(2)
	s_barrier
	global_load_lds_dwordx4 v[8:9], off
	v_lshl_add_u64 v[8:9], v[12:13], 0, s[30:31]
	s_mov_b32 m0, s27
	s_add_i32 s74, s46, 0x8000
	v_lshl_add_u64 v[16:17], s[40:41], 0, v[132:133]
	global_load_lds_dwordx4 v[8:9], off
	v_lshl_add_u64 v[8:9], v[14:15], 0, s[30:31]
	s_mov_b32 m0, s74
	s_add_i32 s75, s46, 0xa000
	v_readlane_b32 s6, v254, 52
	global_load_lds_dwordx4 v[8:9], off
	v_lshl_add_u64 v[8:9], v[16:17], 0, s[30:31]
	s_mov_b32 m0, s75
	s_add_i32 s76, s46, 0x1c000
	v_readlane_b32 s7, v254, 53
	global_load_lds_dwordx4 v[8:9], off
	s_nop 0
	v_lshl_add_u64 v[8:9], s[6:7], 0, v[0:1]
	s_mov_b32 m0, s76
	s_add_i32 s77, s46, 0x1e000
	global_load_lds_dwordx4 v[8:9], off
	v_lshl_add_u64 v[8:9], s[6:7], 0, v[130:131]
	s_mov_b32 m0, s77
	v_or_b32_e32 v143, s8, v18
	global_load_lds_dwordx4 v[8:9], off
	v_lshlrev_b32_e32 v8, 14, v6
	v_and_b32_e32 v8, 0xffff8000, v8
	v_lshl_add_u32 v5, v5, 11, v8
	v_and_b32_e32 v6, 1, v6
	v_lshl_or_b32 v5, v6, 6, v5
	v_lshl_add_u32 v136, v7, 1, v5
	v_lshlrev_b32_e32 v5, 14, v2
	v_and_b32_e32 v5, 0xffff8000, v5
	v_readlane_b32 s8, v254, 38
	s_waitcnt vmcnt(6)
	v_lshl_add_u32 v3, v3, 11, v5
	v_and_b32_e32 v2, 1, v2
	v_readlane_b32 s9, v254, 39
	s_cmpk_lt_u32 s3, 0x100
	v_lshl_or_b32 v2, v2, 6, v3
	s_mov_b32 s49, s8
	v_readlane_b32 s8, v254, 40
	v_readlane_b32 s28, v254, 42
	s_cselect_b64 s[6:7], -1, 0
	v_mov_b32_e32 v137, v1
	v_lshl_add_u32 v138, v4, 1, v2
	v_mov_b32_e32 v139, v1
	s_mov_b32 s48, 0
	s_mov_b32 s78, s8
	v_readlane_b32 s29, v254, 43
	s_barrier
	v_readlane_b32 s9, v254, 41
	s_branch .LBB0_800
.LBB0_564:
	s_mov_b64 s[0:1], 0

; DEVI int next_item(unsigned* ctr, int* slot) {
;     __syncthreads();
;     if (threadIdx.x == 0) *slot = (int)atomicAdd(ctr, 1u);
;     __syncthreads();
;     return *slot;
; }
; __global__ void __launch_bounds__(512) mega(Params p, int ph_lo, int ph_hi, int coop) {
;     ...
;             for (;;) {
;                 const int it = next_item(ctr + 0 + 2 * rep, s_item_p);
;                 if (it >= 2304 + 2064 + 1152) break;
;                 if (it >= 2304 + 2064) { kc_item(p, it - (2304 + 2064)); continue; }
.LBB0_566:
	s_and_saveexec_b64 s[0:1], s[82:83]
	s_mov_b32 s28, 0x3aa2425
	s_cbranch_execz .Ldq2_a
	v_mov_b32_e32 v2, 1
	global_atomic_add v2, v1, v2, s[96:97] sc0
.Ldq2_a:
	s_or_b64 exec, exec, s[0:1]
	s_waitcnt vmcnt(0) lgkmcnt(0)
	s_barrier
	s_and_saveexec_b64 s[0:1], s[82:83]
	s_cbranch_execz .LBB0_570
	ds_write_b32 v175, v2

; DEVI int get_tid() { int t = threadIdx.x; asm volatile("" : "+v"(t)); return t; }
; DEVI void kc_item(const Params& p, int item) {
;     const int tid = get_tid();
;     bf16_t* KC = (bf16_t*)(p.ws + WS_KC);
;     const float* cc = p.in[5]; const float* cp = p.in[6];
; #pragma unroll
;     for (int e = 0; e < 8; ++e) {
;         const long id = (long)item * 4096 + e * 512 + tid;
;         const long rw = id / 36; const int ch = (int)(id - rw * 36);
;         const int b = (int)(rw >> 12), kk = (int)(rw & 4095);
;         const float* src = ch < 32 ? cc + (size_t)rw * 256 + ch * 8 : cp + (size_t)rw * 32 + (ch - 32) * 8;
;         f32x4 a = *(const f32x4*)src, bb = *(const f32x4*)(src + 4);
;         u32x4 w; w.x = pk2(a[0], a[1]); w.y = pk2(a[2], a[3]); w.z = pk2(bb[0], bb[1]); w.w = pk2(bb[2], bb[3]);
;         *(u32x4*)(KC + ((size_t)b * 4112 + kk) * 288 + ch * 8) = w;
.LBB0_765:
	s_andn2_b64 vcc, exec, s[0:1]
	s_cbranch_vccnz .LBB0_564
	v_readlane_b32 s36, v252, 51
	v_readlane_b32 s37, v252, 52
	v_readlane_b32 s38, v252, 53
	v_readlane_b32 s39, v252, 54
	v_readlane_b32 s40, v252, 55
	v_readlane_b32 s41, v252, 56
	v_readlane_b32 s42, v252, 57
	v_readlane_b32 s43, v252, 58
	v_readlane_b32 s44, v252, 59
	v_readlane_b32 s45, v252, 60
	v_readlane_b32 s46, v252, 61
	v_readlane_b32 s47, v252, 62
	v_readlane_b32 s48, v252, 63
	v_readlane_b32 s49, v253, 0
	v_readlane_b32 s50, v253, 1
	v_readlane_b32 s51, v253, 2
	s_lshl_b32 s0, s74, 12
	s_add_i32 s0, s0, 0xfeef0000
	v_add_u32_e32 v2, s0, v180
	s_mov_b32 s1, 0x38e38e39
	v_mov_b32_e32 v16, s46
	v_mov_b32_e32 v17, s47
	v_mov_b32_e32 v18, s48
	v_mov_b32_e32 v19, s49
	v_mul_hi_u32 v4, v2, s1
	v_lshrrev_b32_e32 v4, 3, v4
	v_mul_u32_u24_e32 v5, 36, v4
	v_sub_u32_e32 v5, v2, v5
	v_lshlrev_b32_e32 v6, 10, v4
	v_lshlrev_b32_e32 v7, 7, v4
	v_lshl_add_u32 v6, v5, 5, v6
	v_lshl_add_u32 v7, v5, 5, v7
	v_add_u32_e32 v7, 0xfffffc00, v7
	v_cmp_gt_u32_e32 vcc, 32, v5
	v_lshrrev_b32_e32 v8, 12, v4
	v_and_b32_e32 v9, 0xfff, v4
	v_cndmask_b32_e32 v6, v7, v6, vcc
	v_cndmask_b32_e32 v144, v18, v16, vcc
	v_cndmask_b32_e32 v145, v19, v17, vcc
	v_add_co_u32_e32 v144, vcc, v144, v6
	v_mul_u32_u24_e32 v8, 0x1010, v8
	v_add_u32_e32 v8, v8, v9
	v_addc_co_u32_e32 v145, vcc, 0, v145, vcc
	v_mul_u32_u24_e32 v8, 0x240, v8
	v_lshl_add_u32 v160, v5, 4, v8
	global_load_dwordx4 v[50:53], v[144:145], off
	global_load_dwordx4 v[54:57], v[144:145], off offset:16
	v_add_u32_e32 v3, 512, v2
	v_mul_hi_u32 v4, v3, s1
	v_lshrrev_b32_e32 v4, 3, v4
	v_mul_u32_u24_e32 v5, 36, v4
	v_sub_u32_e32 v5, v3, v5
	v_lshlrev_b32_e32 v6, 10, v4
	v_lshlrev_b32_e32 v7, 7, v4
	v_lshl_add_u32 v6, v5, 5, v6
	v_lshl_add_u32 v7, v5, 5, v7
	v_add_u32_e32 v7, 0xfffffc00, v7
	v_cmp_gt_u32_e32 vcc, 32, v5
	v_lshrrev_b32_e32 v8, 12, v4
	v_and_b32_e32 v9, 0xfff, v4
	v_cndmask_b32_e32 v6, v7, v6, vcc
	v_cndmask_b32_e32 v146, v18, v16, vcc
	v_cndmask_b32_e32 v147, v19, v17, vcc
	v_add_co_u32_e32 v146, vcc, v146, v6
	v_mul_u32_u24_e32 v8, 0x1010, v8
	v_add_u32_e32 v8, v8, v9
	v_addc_co_u32_e32 v147, vcc, 0, v147, vcc
	v_mul_u32_u24_e32 v8, 0x240, v8
	v_lshl_add_u32 v161, v5, 4, v8
	global_load_dwordx4 v[58:61], v[146:147], off
	global_load_dwordx4 v[62:65], v[146:147], off offset:16
	v_add_u32_e32 v3, 1024, v2
	v_mul_hi_u32 v4, v3, s1
	v_lshrrev_b32_e32 v4, 3, v4
	v_mul_u32_u24_e32 v5, 36, v4
	v_sub_u32_e32 v5, v3, v5
	v_lshlrev_b32_e32 v6, 10, v4
	v_lshlrev_b32_e32 v7, 7, v4
	v_lshl_add_u32 v6, v5, 5, v6
	v_lshl_add_u32 v7, v5, 5, v7
	v_add_u32_e32 v7, 0xfffffc00, v7
	v_cmp_gt_u32_e32 vcc, 32, v5
	v_lshrrev_b32_e32 v8, 12, v4
	v_and_b32_e32 v9, 0xfff, v4
	v_cndmask_b32_e32 v6, v7, v6, vcc
	v_cndmask_b32_e32 v148, v18, v16, vcc
	v_cndmask_b32_e32 v149, v19, v17, vcc
	v_add_co_u32_e32 v148, vcc, v148, v6
	v_mul_u32_u24_e32 v8, 0x1010, v8
	v_add_u32_e32 v8, v8, v9
	v_addc_co_u32_e32 v149, vcc, 0, v149, vcc
	v_mul_u32_u24_e32 v8, 0x240, v8
	v_lshl_add_u32 v162, v5, 4, v8
	global_load_dwordx4 v[66:69], v[148:149], off
	global_load_dwordx4 v[70:73], v[148:149], off offset:16
	v_add_u32_e32 v3, 1536, v2
	v_mul_hi_u32 v4, v3, s1
	v_lshrrev_b32_e32 v4, 3, v4
	v_mul_u32_u24_e32 v5, 36, v4
	v_sub_u32_e32 v5, v3, v5
	v_lshlrev_b32_e32 v6, 10, v4
	v_lshlrev_b32_e32 v7, 7, v4
	v_lshl_add_u32 v6, v5, 5, v6
	v_lshl_add_u32 v7, v5, 5, v7
	v_add_u32_e32 v7, 0xfffffc00, v7
	v_cmp_gt_u32_e32 vcc, 32, v5
	v_lshrrev_b32_e32 v8, 12, v4
	v_and_b32_e32 v9, 0xfff, v4
	v_cndmask_b32_e32 v6, v7, v6, vcc
	v_cndmask_b32_e32 v150, v18, v16, vcc
	v_cndmask_b32_e32 v151, v19, v17, vcc
	v_add_co_u32_e32 v150, vcc, v150, v6
	v_mul_u32_u24_e32 v8, 0x1010, v8
	v_add_u32_e32 v8, v8, v9
	v_addc_co_u32_e32 v151, vcc, 0, v151, vcc
	v_mul_u32_u24_e32 v8, 0x240, v8
	v_lshl_add_u32 v163, v5, 4, v8
	global_load_dwordx4 v[74:77], v[150:151], off
	global_load_dwordx4 v[78:81], v[150:151], off offset:16
	v_add_u32_e32 v3, 2048, v2
	v_mul_hi_u32 v4, v3, s1
	v_lshrrev_b32_e32 v4, 3, v4
	v_mul_u32_u24_e32 v5, 36, v4
	v_sub_u32_e32 v5, v3, v5
	v_lshlrev_b32_e32 v6, 10, v4
	v_lshlrev_b32_e32 v7, 7, v4
	v_lshl_add_u32 v6, v5, 5, v6
	v_lshl_add_u32 v7, v5, 5, v7
	v_add_u32_e32 v7, 0xfffffc00, v7
	v_cmp_gt_u32_e32 vcc, 32, v5
	v_lshrrev_b32_e32 v8, 12, v4
	v_and_b32_e32 v9, 0xfff, v4
	v_cndmask_b32_e32 v6, v7, v6, vcc
	v_cndmask_b32_e32 v152, v18, v16, vcc
; DEVI void kc_item(const Params& p, int item) {
;     ...
;     for (int e = 0; e < 8; ++e) {
;         const long id = (long)item * 4096 + e * 512 + tid;
;         const long rw = id / 36; const int ch = (int)(id - rw * 36);
;         const int b = (int)(rw >> 12), kk = (int)(rw & 4095);
;         const float* src = ch < 32 ? cc + (size_t)rw * 256 + ch * 8 : cp + (size_t)rw * 32 + (ch - 32) * 8;
;         f32x4 a = *(const f32x4*)src, bb = *(const f32x4*)(src + 4);
;         u32x4 w; w.x = pk2(a[0], a[1]); w.y = pk2(a[2], a[3]); w.z = pk2(bb[0], bb[1]); w.w = pk2(bb[2], bb[3]);
;         *(u32x4*)(KC + ((size_t)b * 4112 + kk) * 288 + ch * 8) = w;
;     }
	v_cndmask_b32_e32 v153, v19, v17, vcc
	v_add_co_u32_e32 v152, vcc, v152, v6
	v_mul_u32_u24_e32 v8, 0x1010, v8
	v_add_u32_e32 v8, v8, v9
	v_addc_co_u32_e32 v153, vcc, 0, v153, vcc
	v_mul_u32_u24_e32 v8, 0x240, v8
	v_lshl_add_u32 v164, v5, 4, v8
	global_load_dwordx4 v[82:85], v[152:153], off
	global_load_dwordx4 v[86:89], v[152:153], off offset:16
	v_add_u32_e32 v3, 2560, v2
	v_mul_hi_u32 v4, v3, s1
	v_lshrrev_b32_e32 v4, 3, v4
	v_mul_u32_u24_e32 v5, 36, v4
	v_sub_u32_e32 v5, v3, v5
	v_lshlrev_b32_e32 v6, 10, v4
	v_lshlrev_b32_e32 v7, 7, v4
	v_lshl_add_u32 v6, v5, 5, v6
	v_lshl_add_u32 v7, v5, 5, v7
	v_add_u32_e32 v7, 0xfffffc00, v7
	v_cmp_gt_u32_e32 vcc, 32, v5
	v_lshrrev_b32_e32 v8, 12, v4
	v_and_b32_e32 v9, 0xfff, v4
	v_cndmask_b32_e32 v6, v7, v6, vcc
	v_cndmask_b32_e32 v154, v18, v16, vcc
	v_cndmask_b32_e32 v155, v19, v17, vcc
	v_add_co_u32_e32 v154, vcc, v154, v6
	v_mul_u32_u24_e32 v8, 0x1010, v8
	v_add_u32_e32 v8, v8, v9
	v_addc_co_u32_e32 v155, vcc, 0, v155, vcc
	v_mul_u32_u24_e32 v8, 0x240, v8
	v_lshl_add_u32 v165, v5, 4, v8
	global_load_dwordx4 v[90:93], v[154:155], off
	global_load_dwordx4 v[94:97], v[154:155], off offset:16
	v_add_u32_e32 v3, 3072, v2
	v_mul_hi_u32 v4, v3, s1
	v_lshrrev_b32_e32 v4, 3, v4
	v_mul_u32_u24_e32 v5, 36, v4
	v_sub_u32_e32 v5, v3, v5
	v_lshlrev_b32_e32 v6, 10, v4
	v_lshlrev_b32_e32 v7, 7, v4
	v_lshl_add_u32 v6, v5, 5, v6
	v_lshl_add_u32 v7, v5, 5, v7
	v_add_u32_e32 v7, 0xfffffc00, v7
	v_cmp_gt_u32_e32 vcc, 32, v5
	v_lshrrev_b32_e32 v8, 12, v4
	v_and_b32_e32 v9, 0xfff, v4
	v_cndmask_b32_e32 v6, v7, v6, vcc
	v_cndmask_b32_e32 v156, v18, v16, vcc
	v_cndmask_b32_e32 v157, v19, v17, vcc
	v_add_co_u32_e32 v156, vcc, v156, v6
	v_mul_u32_u24_e32 v8, 0x1010, v8
	v_add_u32_e32 v8, v8, v9
	v_addc_co_u32_e32 v157, vcc, 0, v157, vcc
	v_mul_u32_u24_e32 v8, 0x240, v8
	v_lshl_add_u32 v166, v5, 4, v8
	global_load_dwordx4 v[98:101], v[156:157], off
	global_load_dwordx4 v[102:105], v[156:157], off offset:16
	v_add_u32_e32 v3, 3584, v2
	v_mul_hi_u32 v4, v3, s1
	v_lshrrev_b32_e32 v4, 3, v4
	v_mul_u32_u24_e32 v5, 36, v4
	v_sub_u32_e32 v5, v3, v5
	v_lshlrev_b32_e32 v6, 10, v4
	v_lshlrev_b32_e32 v7, 7, v4
	v_lshl_add_u32 v6, v5, 5, v6
	v_lshl_add_u32 v7, v5, 5, v7
	v_add_u32_e32 v7, 0xfffffc00, v7
	v_cmp_gt_u32_e32 vcc, 32, v5
	v_lshrrev_b32_e32 v8, 12, v4
	v_and_b32_e32 v9, 0xfff, v4
	v_cndmask_b32_e32 v6, v7, v6, vcc
	v_cndmask_b32_e32 v158, v18, v16, vcc
	v_cndmask_b32_e32 v159, v19, v17, vcc
	v_add_co_u32_e32 v158, vcc, v158, v6
	v_mul_u32_u24_e32 v8, 0x1010, v8
	v_add_u32_e32 v8, v8, v9
	v_addc_co_u32_e32 v159, vcc, 0, v159, vcc
	v_mul_u32_u24_e32 v8, 0x240, v8
	v_lshl_add_u32 v167, v5, 4, v8
	global_load_dwordx4 v[188:191], v[158:159], off
	global_load_dwordx4 v[192:195], v[158:159], off offset:16
	s_waitcnt vmcnt(14)
	v_cvt_pk_bf16_f32 v50, v50, v51
	v_cvt_pk_bf16_f32 v51, v52, v53
	v_cvt_pk_bf16_f32 v52, v54, v55
	v_cvt_pk_bf16_f32 v53, v56, v57
	global_store_dwordx4 v160, v[50:53], s[94:95]
	s_waitcnt vmcnt(12)
	v_cvt_pk_bf16_f32 v58, v58, v59
	v_cvt_pk_bf16_f32 v59, v60, v61
	v_cvt_pk_bf16_f32 v60, v62, v63
	v_cvt_pk_bf16_f32 v61, v64, v65
	global_store_dwordx4 v161, v[58:61], s[94:95]
	s_waitcnt vmcnt(10)
	v_cvt_pk_bf16_f32 v66, v66, v67
	v_cvt_pk_bf16_f32 v67, v68, v69
	v_cvt_pk_bf16_f32 v68, v70, v71
	v_cvt_pk_bf16_f32 v69, v72, v73
	global_store_dwordx4 v162, v[66:69], s[94:95]
	s_waitcnt vmcnt(8)
	v_cvt_pk_bf16_f32 v74, v74, v75
	v_cvt_pk_bf16_f32 v75, v76, v77
	v_cvt_pk_bf16_f32 v76, v78, v79
	v_cvt_pk_bf16_f32 v77, v80, v81
	global_store_dwordx4 v163, v[74:77], s[94:95]
	s_waitcnt vmcnt(6)
	v_cvt_pk_bf16_f32 v82, v82, v83
	v_cvt_pk_bf16_f32 v83, v84, v85
	v_cvt_pk_bf16_f32 v84, v86, v87
	v_cvt_pk_bf16_f32 v85, v88, v89
	global_store_dwordx4 v164, v[82:85], s[94:95]
	s_waitcnt vmcnt(4)
	v_cvt_pk_bf16_f32 v90, v90, v91
	v_cvt_pk_bf16_f32 v91, v92, v93
	v_cvt_pk_bf16_f32 v92, v94, v95
	v_cvt_pk_bf16_f32 v93, v96, v97
	global_store_dwordx4 v165, v[90:93], s[94:95]
	s_waitcnt vmcnt(2)
	v_cvt_pk_bf16_f32 v98, v98, v99
	v_cvt_pk_bf16_f32 v99, v100, v101
	v_cvt_pk_bf16_f32 v100, v102, v103
	v_cvt_pk_bf16_f32 v101, v104, v105
	global_store_dwordx4 v166, v[98:101], s[94:95]
	s_waitcnt vmcnt(0)
	v_cvt_pk_bf16_f32 v188, v188, v189
	v_cvt_pk_bf16_f32 v189, v190, v191
	v_cvt_pk_bf16_f32 v190, v192, v193
	v_cvt_pk_bf16_f32 v191, v194, v195
	global_store_dwordx4 v167, v[188:191], s[94:95]
	s_branch .LBB0_564

; DEVI void phase_prep(const Params& p, float* lds) {
;     ...
;     {
;         bf16_t* dst = (bf16_t*)(p.ws + WS_WQLT);
;         const float* wuq = p.in[21];
;         const float* wuk = p.in[22];
;         for (int i = gtid; i < 2048 * 384; i += gsz) {
;             int c = i & 255, h = (i >> 8) & 7, j = i >> 11;
;             const float* a = wuq + (size_t)j * 768 + h * 96;
;             const float* b = wuk + (size_t)h * 64 * 256 + c;
;             float s = 0.f;
; #pragma unroll 8
;             for (int n = 0; n < 64; ++n) s += a[n] * b[(size_t)n * 256];
.LBB0_875:
	v_bfe_u32 v3, v2, 8, 3
	v_lshlrev_b32_e32 v0, 16, v3
	v_ashrrev_i32_e32 v6, 11, v2
	v_readlane_b32 s48, v251, 0
	v_lshl_add_u64 v[8:9], v[4:5], 0, v[0:1]
	v_mul_hi_i32_i24_e32 v11, 0xc00, v6
	v_mul_i32_i24_e32 v10, 0xc00, v6
	v_readlane_b32 s58, v251, 10
	v_readlane_b32 s59, v251, 11
	v_mul_u32_u24_e32 v0, 0x60, v3
	v_lshlrev_b32_e32 v0, 2, v0
	v_lshl_add_u64 v[10:11], s[58:59], 0, v[10:11]
	v_lshl_add_u64 v[10:11], v[10:11], 0, v[0:1]
	v_mov_b32_e32 v0, 0
	s_mov_b64 s[14:15], 0
	v_readlane_b32 s49, v251, 1
	v_readlane_b32 s50, v251, 2
	v_readlane_b32 s51, v251, 3
	v_readlane_b32 s52, v251, 4
	v_readlane_b32 s53, v251, 5
	v_readlane_b32 s54, v251, 6
	v_readlane_b32 s55, v251, 7
	v_readlane_b32 s56, v251, 8
	v_readlane_b32 s57, v251, 9
	v_readlane_b32 s60, v251, 12
	v_readlane_b32 s61, v251, 13
	v_readlane_b32 s62, v251, 14
	v_readlane_b32 s63, v251, 15
	s_mov_b32 s14, 0xfffff200
	s_mov_b32 s15, -1
	s_mov_b64 s[16:17], 0x2000
	v_lshl_add_u64 v[144:145], v[8:9], 0, s[14:15]
	v_lshl_add_u64 v[146:147], v[144:145], 0, s[16:17]
	v_lshl_add_u64 v[148:149], v[146:147], 0, s[16:17]
	v_lshl_add_u64 v[150:151], v[148:149], 0, s[16:17]
	v_lshl_add_u64 v[158:159], v[150:151], 0, s[16:17]
	v_lshl_add_u64 v[160:161], v[158:159], 0, s[16:17]
	v_lshl_add_u64 v[162:163], v[160:161], 0, s[16:17]
	v_lshl_add_u64 v[164:165], v[162:163], 0, s[16:17]
	global_load_dwordx4 v[50:53], v[10:11], off
	global_load_dwordx4 v[54:57], v[10:11], off offset:16
	global_load_dwordx4 v[58:61], v[10:11], off offset:32
	global_load_dwordx4 v[62:65], v[10:11], off offset:48
	global_load_dwordx4 v[66:69], v[10:11], off offset:64
	global_load_dwordx4 v[70:73], v[10:11], off offset:80
	global_load_dwordx4 v[74:77], v[10:11], off offset:96
	global_load_dwordx4 v[78:81], v[10:11], off offset:112
	global_load_dword v82, v[144:145], off offset:-3584
	global_load_dword v83, v[144:145], off offset:-2560
	global_load_dword v84, v[144:145], off offset:-1536
	global_load_dword v85, v[144:145], off offset:-512
	global_load_dword v86, v[144:145], off offset:512
	global_load_dword v87, v[144:145], off offset:1536
	global_load_dword v88, v[144:145], off offset:2560
	global_load_dword v89, v[144:145], off offset:3584
	global_load_dword v90, v[146:147], off offset:-3584
	global_load_dword v91, v[146:147], off offset:-2560
	global_load_dword v92, v[146:147], off offset:-1536
	global_load_dword v93, v[146:147], off offset:-512
	global_load_dword v94, v[146:147], off offset:512
	global_load_dword v95, v[146:147], off offset:1536
	global_load_dword v96, v[146:147], off offset:2560
	global_load_dword v97, v[146:147], off offset:3584
	global_load_dword v98, v[148:149], off offset:-3584
	global_load_dword v99, v[148:149], off offset:-2560
	global_load_dword v100, v[148:149], off offset:-1536
	global_load_dword v101, v[148:149], off offset:-512
	global_load_dword v102, v[148:149], off offset:512
	global_load_dword v103, v[148:149], off offset:1536
	global_load_dword v104, v[148:149], off offset:2560
	global_load_dword v105, v[148:149], off offset:3584
	global_load_dword v106, v[150:151], off offset:-3584
	global_load_dword v107, v[150:151], off offset:-2560
	global_load_dword v108, v[150:151], off offset:-1536
	global_load_dword v109, v[150:151], off offset:-512
	global_load_dword v112, v[150:151], off offset:512
	global_load_dword v113, v[150:151], off offset:1536
	global_load_dword v114, v[150:151], off offset:2560
	global_load_dword v115, v[150:151], off offset:3584
	s_waitcnt vmcnt(20)
; DEVI void phase_prep(const Params& p, float* lds) {
;     ...
;         for (int i = gtid; i < 2048 * 384; i += gsz) {
;             int c = i & 255, h = (i >> 8) & 7, j = i >> 11;
;             const float* a = wuq + (size_t)j * 768 + h * 96;
;             const float* b = wuk + (size_t)h * 64 * 256 + c;
;             float s = 0.f;
; #pragma unroll 8
;             for (int n = 0; n < 64; ++n) s += a[n] * b[(size_t)n * 256];
;             dst[(size_t)(h * 256 + c) * 384 + j] = f2bf(s * MLQ);
;         }
	global_load_dwordx4 v[188:191], v[10:11], off offset:128
	global_load_dwordx4 v[192:195], v[10:11], off offset:144
	global_load_dwordx4 v[196:199], v[10:11], off offset:160
	global_load_dwordx4 v[200:203], v[10:11], off offset:176
	global_load_dwordx4 v[204:207], v[10:11], off offset:192
	global_load_dwordx4 v[208:211], v[10:11], off offset:208
	global_load_dwordx4 v[212:215], v[10:11], off offset:224
	global_load_dwordx4 v[216:219], v[10:11], off offset:240
	global_load_dword v220, v[158:159], off offset:-3584
	global_load_dword v221, v[158:159], off offset:-2560
	global_load_dword v222, v[158:159], off offset:-1536
	global_load_dword v223, v[158:159], off offset:-512
	global_load_dword v224, v[158:159], off offset:512
	global_load_dword v225, v[158:159], off offset:1536
	global_load_dword v226, v[158:159], off offset:2560
	global_load_dword v227, v[158:159], off offset:3584
	global_load_dword v228, v[160:161], off offset:-3584
	global_load_dword v229, v[160:161], off offset:-2560
	global_load_dword v230, v[160:161], off offset:-1536
	global_load_dword v231, v[160:161], off offset:-512
	global_load_dword v232, v[160:161], off offset:512
	global_load_dword v233, v[160:161], off offset:1536
	global_load_dword v234, v[160:161], off offset:2560
	global_load_dword v235, v[160:161], off offset:3584
	global_load_dword v236, v[162:163], off offset:-3584
	global_load_dword v237, v[162:163], off offset:-2560
	global_load_dword v238, v[162:163], off offset:-1536
	global_load_dword v239, v[162:163], off offset:-512
	global_load_dword v240, v[162:163], off offset:512
	global_load_dword v241, v[162:163], off offset:1536
	global_load_dword v242, v[162:163], off offset:2560
	global_load_dword v243, v[162:163], off offset:3584
	global_load_dword v244, v[164:165], off offset:-3584
	global_load_dword v245, v[164:165], off offset:-2560
	global_load_dword v152, v[164:165], off offset:-1536
	global_load_dword v153, v[164:165], off offset:-512
	global_load_dword v154, v[164:165], off offset:512
	global_load_dword v155, v[164:165], off offset:1536
	global_load_dword v156, v[164:165], off offset:2560
	global_load_dword v157, v[164:165], off offset:3584
	s_waitcnt vmcnt(40)
	v_fmac_f32_e32 v0, v50, v82
	v_fmac_f32_e32 v0, v51, v83
	v_fmac_f32_e32 v0, v52, v84
	v_fmac_f32_e32 v0, v53, v85
	v_fmac_f32_e32 v0, v54, v86
	v_fmac_f32_e32 v0, v55, v87
	v_fmac_f32_e32 v0, v56, v88
	v_fmac_f32_e32 v0, v57, v89
	v_fmac_f32_e32 v0, v58, v90
	v_fmac_f32_e32 v0, v59, v91
	v_fmac_f32_e32 v0, v60, v92
	v_fmac_f32_e32 v0, v61, v93
	v_fmac_f32_e32 v0, v62, v94
	v_fmac_f32_e32 v0, v63, v95
	v_fmac_f32_e32 v0, v64, v96
	v_fmac_f32_e32 v0, v65, v97
	v_fmac_f32_e32 v0, v66, v98
	v_fmac_f32_e32 v0, v67, v99
	v_fmac_f32_e32 v0, v68, v100
	v_fmac_f32_e32 v0, v69, v101
	v_fmac_f32_e32 v0, v70, v102
	v_fmac_f32_e32 v0, v71, v103
	v_fmac_f32_e32 v0, v72, v104
	v_fmac_f32_e32 v0, v73, v105
	v_fmac_f32_e32 v0, v74, v106
	v_fmac_f32_e32 v0, v75, v107
	v_fmac_f32_e32 v0, v76, v108
	v_fmac_f32_e32 v0, v77, v109
	v_fmac_f32_e32 v0, v78, v112
	v_fmac_f32_e32 v0, v79, v113
	v_fmac_f32_e32 v0, v80, v114
	v_fmac_f32_e32 v0, v81, v115
	s_waitcnt vmcnt(0)
	v_fmac_f32_e32 v0, v188, v220
	v_fmac_f32_e32 v0, v189, v221
	v_fmac_f32_e32 v0, v190, v222
	v_fmac_f32_e32 v0, v191, v223
	v_fmac_f32_e32 v0, v192, v224
	v_fmac_f32_e32 v0, v193, v225
	v_fmac_f32_e32 v0, v194, v226
	v_fmac_f32_e32 v0, v195, v227
	v_fmac_f32_e32 v0, v196, v228
	v_fmac_f32_e32 v0, v197, v229
	v_fmac_f32_e32 v0, v198, v230
	v_fmac_f32_e32 v0, v199, v231
	v_fmac_f32_e32 v0, v200, v232
	v_fmac_f32_e32 v0, v201, v233
	v_fmac_f32_e32 v0, v202, v234
	v_fmac_f32_e32 v0, v203, v235
	v_fmac_f32_e32 v0, v204, v236
	v_fmac_f32_e32 v0, v205, v237
	v_fmac_f32_e32 v0, v206, v238
	v_fmac_f32_e32 v0, v207, v239
	v_fmac_f32_e32 v0, v208, v240
	v_fmac_f32_e32 v0, v209, v241
	v_fmac_f32_e32 v0, v210, v242
	v_fmac_f32_e32 v0, v211, v243
	v_fmac_f32_e32 v0, v212, v244
	v_fmac_f32_e32 v0, v213, v245
	v_fmac_f32_e32 v0, v214, v152
	v_fmac_f32_e32 v0, v215, v153
	v_fmac_f32_e32 v0, v216, v154
	v_fmac_f32_e32 v0, v217, v155
	v_fmac_f32_e32 v0, v218, v156
	v_fmac_f32_e32 v0, v219, v157
	v_mul_f32_e32 v0, 0x3e16c740, v0
	v_cvt_pk_bf16_f32 v3, v0, s0
	v_and_b32_e32 v0, 0x7ff, v2
	v_mul_u32_u24_e32 v0, 0x180, v0
	v_readlane_b32 s14, v252, 22
	v_lshlrev_b32_e32 v0, 1, v0
	v_readlane_b32 s15, v252, 23
	v_add_u32_e32 v2, s0, v2
	s_mov_b32 s1, 0xbffff
	v_ashrrev_i32_e32 v7, 31, v6
	v_lshl_add_u64 v[8:9], s[14:15], 0, v[0:1]
	v_cmp_lt_i32_e32 vcc, s1, v2
	v_lshl_add_u64 v[6:7], v[6:7], 1, v[8:9]
	s_or_b64 s[8:9], vcc, s[8:9]
	global_store_short v[6:7], v3, off
	s_andn2_b64 exec, exec, s[8:9]
	s_cbranch_execnz .LBB0_875
